# speedup vs baseline: 1.0772x; 1.0180x over previous
; __device__ __forceinline__ int otid() { int t; asm volatile("v_mov_b32 %0, %1" : "=v"(t) : "v"((int)threadIdx.x)); return t; }
; #define SETPTR(IT) { const int mt_ = ITEM_MT(IT), nt_ = ITEM_NT(IT); ga = A + (size_t)(mt_ * AROWS + srow) * lda + (skc ^ fs) * 8; gb = Bt + (size_t)(nt_ * 256 + srow) * ldb + (skc ^ fs) * 8; }
; #define ADV() { ga += 32; gb += 32; ck += 32; if (ck == K) { ck = 0; citem += gridDim.x; const int ci_ = citem < total ? citem : total - 1; SETPTR(ci_) } }
; #define WAITSTEP() { if (a2) WAITV(4); else WAITV(3); }
;     ...
;   const int tid = otid(), lane = tid & 63, wid = tid >> 6, wm = wid >> 2, wn = wid & 3, l15 = lane & 15, quad = lane >> 4;
;   const int srow = tid >> 2, skc = tid & 3;
;   constexpr int AROWS = MI * 32, ABYTES = AROWS * 64, STAGE = ABYTES + 16384;
;   constexpr int GRP = 4;
;   const int fr = (-(l15 >> 2)) & 3, fs = (-(srow >> 2)) & 3;
;   const int aoff = (wm * (MI * 16) + l15) * 64 + (quad ^ fr) * 16, boff = ABYTES + (wn * 64 + l15) * 64 + (quad ^ fr) * 16;
;   const int nk = K >> 5;
;   const bool a2 = (MI != 4);
;   const int a2row = (MI == 6 && tid >= 256) ? 64 : 128, a2lds = (MI == 6 && tid >= 256) ? 4096 : 8192;
;   int citem = item, ck = 0;
;   const u16* ga; const u16* gb;
;     ...
;   SETPTR(citem)
;   GLDS(0) ADV()
;   GLDS(STAGE) ADV()
;   WAITSTEP()
;   __builtin_amdgcn_s_barrier();
;   int scur = 0, snext = 2 * STAGE;
.LBB0_203:
	s_or_b64 exec, exec, s[4:5]
	s_andn2_b64 vcc, exec, s[0:1]
	s_mov_b64 s[6:7], -1
	s_barrier
	s_cbranch_vccnz .LBB0_246
	v_readlane_b32 s0, v255, 54
	s_lshr_b32 s3, s0, 1
	s_mul_i32 s0, s3, 0x1080000
	v_readlane_b32 s1, v255, 33
	v_readlane_b32 s4, v254, 17
	s_add_u32 s0, s1, s0
	v_readlane_b32 s1, v255, 34
	v_readlane_b32 s5, v254, 18
	s_addc_u32 s1, s1, 0
	s_andn2_b64 vcc, exec, s[4:5]
	s_cbranch_vccnz .LBB0_213
	v_mov_b32 v8, v200
	v_readlane_b32 s4, v254, 19
	v_ashrrev_i32_e32 v131, 2, v8
	v_lshrrev_b32_e32 v0, 4, v8
	v_sub_u32_e32 v2, 0, v0
	v_add_u32_e32 v0, s4, v131
	v_ashrrev_i32_e32 v1, 31, v0
	v_readlane_b32 s6, v254, 11
	v_xor_b32_e32 v2, v8, v2
	v_lshlrev_b64 v[0:1], 11, v[0:1]
	v_readlane_b32 s7, v254, 12
	v_lshlrev_b32_e32 v2, 4, v2
	v_readlane_b32 s4, v254, 20
	v_lshl_add_u32 v142, v8, 4, 0
	v_lshl_add_u64 v[0:1], s[6:7], 0, v[0:1]
	v_and_b32_e32 v128, 48, v2
	v_add_u32_e32 v2, s4, v131
	v_readfirstlane_b32 s4, v142
	v_readfirstlane_b32 s100, v142
	v_add_u32_e32 v6, 0x2000, v142
	v_lshl_add_u64 v[0:1], v[0:1], 0, v[128:129]
	s_mov_b32 m0, s4
	v_readfirstlane_b32 s4, v6
	v_ashrrev_i32_e32 v3, 31, v2
	global_load_lds_dwordx4 v[0:1], off
	v_lshl_add_u64 v[4:5], v[0:1], 0, s[50:51]
	s_mov_b32 m0, s4
	v_lshlrev_b64 v[2:3], 11, v[2:3]
	global_load_lds_dwordx4 v[4:5], off
	v_add_u32_e32 v4, 0x4000, v142
	v_lshl_add_u64 v[2:3], s[0:1], 0, v[2:3]
	v_readfirstlane_b32 s4, v4
	v_add_u32_e32 v6, 0x6000, v142
	v_lshl_add_u64 v[2:3], v[2:3], 0, v[128:129]
	s_mov_b32 m0, s4
	v_readfirstlane_b32 s4, v6
	v_add_u32_e32 v9, 0x8000, v142
	global_load_lds_dwordx4 v[2:3], off
	v_lshl_add_u64 v[4:5], v[2:3], 0, s[50:51]
	s_mov_b32 m0, s4
	v_readfirstlane_b32 s4, v9
	v_add_u32_e32 v9, 0xa000, v142
	global_load_lds_dwordx4 v[4:5], off
	v_lshl_add_u64 v[6:7], v[0:1], 0, 64
	s_mov_b32 m0, s4
	s_mov_b64 s[8:9], 0x40040
	v_readfirstlane_b32 s4, v9
	global_load_lds_dwordx4 v[6:7], off
	v_lshl_add_u64 v[6:7], v[0:1], 0, s[8:9]
	s_mov_b32 m0, s4
	v_lshl_add_u64 v[4:5], v[2:3], 0, 64
	global_load_lds_dwordx4 v[6:7], off
	v_add_u32_e32 v6, 0xc000, v142
	s_mov_b32 s5, 0x3ffff80
	v_readfirstlane_b32 s4, v6
	v_add_u32_e32 v6, 0xe000, v142
	s_mov_b32 m0, s4
	v_readfirstlane_b32 s4, v6
	global_load_lds_dwordx4 v[4:5], off
	v_lshl_add_u64 v[4:5], v[2:3], 0, s[8:9]
	s_mov_b32 m0, s4
	s_mov_b64 s[8:9], 0x80
	global_load_lds_dwordx4 v[4:5], off
	v_and_b32_e32 v4, 15, v8
	v_lshrrev_b32_e32 v5, 1, v8
	v_and_or_b32 v4, v5, s5, v4
	v_lshlrev_b32_e32 v143, 6, v4
	v_lshlrev_b32_e32 v4, 2, v8
	v_and_b32_e32 v4, 48, v4
	v_sub_u32_e32 v4, 0, v4
	s_waitcnt vmcnt(4)
	v_bitop3_b32 v144, v8, 48, v4 bitop3:0x48
	v_lshlrev_b32_e32 v4, 6, v8
	v_lshl_add_u64 v[132:133], s[6:7], 0, v[128:129]
	v_readlane_b32 s7, v255, 12
	s_mov_b32 s4, 0
	v_and_b32_e32 v145, 0x33c0, v4
	v_lshl_add_u64 v[138:139], v[2:3], 0, s[8:9]
	v_lshl_add_u64 v[136:137], v[0:1], 0, s[8:9]
	v_lshl_add_u64 v[134:135], s[0:1], 0, v[128:129]
	s_mov_b32 s8, 64
	s_mov_b32 s5, 0x10000
	s_mov_b32 s6, s7
	s_barrier
	s_branch .LBB0_207

; #define MFMA(a, b, c) __builtin_amdgcn_mfma_f32_16x16x32_bf16((a), (b), (c), 0, 0, 0)
; #define ADV() { ga += 32; gb += 32; ck += 32; if (ck == K) { ck = 0; citem += gridDim.x; const int ci_ = citem < total ? citem : total - 1; SETPTR(ci_) } }
; #define WAITSTEP() { if (a2) WAITV(4); else WAITV(3); }
;     ...
;     for (int kt = 0; kt < nk; ++kt) {
;       if (VAR != 1) { const char* base = lds + scur; bf16x8 a[MI], b[4];
; #pragma unroll
;         for (int i = 0; i < 4; ++i) b[i] = *(const bf16x8*)(base + boff + i * 1024);
; #pragma unroll
;         for (int i = 0; i < MI; ++i) a[i] = *(const bf16x8*)(base + aoff + i * 1024);
; #pragma unroll
;         for (int i = 0; i < MI; ++i)
; #pragma unroll
;           for (int j = 0; j < 4; ++j) acc[i][j] = MFMA(a[i], b[j], acc[i][j]);
;         if (VAR != 2) GLDS(snext)
;     ...
;         if (MI == 8) {
;           __builtin_amdgcn_sched_group_barrier(0x100, MI + 4, 0);
; #pragma unroll
;           for (int g = 0; g < 4; ++g) { __builtin_amdgcn_sched_group_barrier(0x008, 7, 0); __builtin_amdgcn_sched_group_barrier(0x010, 1, 0); }
;           __builtin_amdgcn_sched_group_barrier(0x008, 4, 0);
;         } else if (MI == 6) {
;           __builtin_amdgcn_sched_group_barrier(0x100, MI + 4, 0);
; #pragma unroll
;           for (int g = 0; g < 4; ++g) { __builtin_amdgcn_sched_group_barrier(0x008, 5, 0); __builtin_amdgcn_sched_group_barrier(0x010, 1, 0); }
;           __builtin_amdgcn_sched_group_barrier(0x008, 4, 0);
;         }
;     ...
;       }
;       ADV()
;       if (VAR == 2) {} else WAITSTEP()
;       __builtin_amdgcn_s_barrier();
;       scur = (scur == 2 * STAGE) ? 0 : scur + STAGE;
;       snext = (snext == 2 * STAGE) ? 0 : snext + STAGE;
.LBB0_210:
	s_cmpk_ge_u32 s100, 0x1000
	s_cbranch_scc1 .Lffn8_hi
	s_add_i32 s62, s4, 0
	v_add3_u32 v140, s62, v143, v144
	v_add3_u32 v128, s62, v145, v144
	ds_read_b128 v[158:161], v140
	ds_read_b128 v[146:149], v128 offset:16384
	ds_read_b128 v[150:153], v128 offset:17408
	ds_read_b128 v[154:157], v128 offset:18432
	ds_read_b128 v[162:165], v128 offset:19456
	ds_read_b128 v[166:169], v140 offset:1024
	ds_read_b128 v[170:173], v140 offset:2048
	ds_read_b128 v[174:177], v140 offset:3072
	ds_read_b128 v[178:181], v140 offset:4096
	ds_read_b128 v[182:185], v140 offset:5120
	ds_read_b128 v[186:189], v140 offset:6144
	ds_read_b128 v[190:193], v140 offset:7168
	s_add_i32 s62, s5, s100
	s_mov_b32 m0, s62
	v_lshl_add_u64 v[194:195], v[136:137], 0, s[50:51]
	v_lshl_add_u64 v[196:197], v[138:139], 0, s[50:51]
	s_nop 0
	global_load_lds_dwordx4 v[136:137], off
	s_add_i32 m0, s62, 0x2000
	s_nop 0
	global_load_lds_dwordx4 v[194:195], off
	s_add_i32 m0, s62, 0x4000
	s_nop 0
	global_load_lds_dwordx4 v[138:139], off
	s_add_i32 m0, s62, 0x6000
	s_nop 0
	global_load_lds_dwordx4 v[196:197], off
	s_waitcnt lgkmcnt(10)
	v_mfma_f32_16x16x32_bf16 v[124:127], v[158:161], v[146:149], v[124:127]
	s_waitcnt lgkmcnt(9)
	v_mfma_f32_16x16x32_bf16 v[120:123], v[158:161], v[150:153], v[120:123]
	s_waitcnt lgkmcnt(8)
	v_mfma_f32_16x16x32_bf16 v[116:119], v[158:161], v[154:157], v[116:119]
	s_waitcnt lgkmcnt(7)
	v_mfma_f32_16x16x32_bf16 v[112:115], v[158:161], v[162:165], v[112:115]
	s_waitcnt lgkmcnt(6)
	v_mfma_f32_16x16x32_bf16 v[108:111], v[166:169], v[146:149], v[108:111]
	v_mfma_f32_16x16x32_bf16 v[104:107], v[166:169], v[150:153], v[104:107]
	v_mfma_f32_16x16x32_bf16 v[100:103], v[166:169], v[154:157], v[100:103]
	v_mfma_f32_16x16x32_bf16 v[96:99], v[166:169], v[162:165], v[96:99]
	s_waitcnt lgkmcnt(5)
	v_mfma_f32_16x16x32_bf16 v[92:95], v[170:173], v[146:149], v[92:95]
	v_mfma_f32_16x16x32_bf16 v[88:91], v[170:173], v[150:153], v[88:91]
	v_mfma_f32_16x16x32_bf16 v[84:87], v[170:173], v[154:157], v[84:87]
	v_mfma_f32_16x16x32_bf16 v[80:83], v[170:173], v[162:165], v[80:83]
	s_waitcnt lgkmcnt(4)
	v_mfma_f32_16x16x32_bf16 v[76:79], v[174:177], v[146:149], v[76:79]
	v_mfma_f32_16x16x32_bf16 v[72:75], v[174:177], v[150:153], v[72:75]
	v_mfma_f32_16x16x32_bf16 v[68:71], v[174:177], v[154:157], v[68:71]
	v_mfma_f32_16x16x32_bf16 v[64:67], v[174:177], v[162:165], v[64:67]
	s_waitcnt lgkmcnt(3)
	v_mfma_f32_16x16x32_bf16 v[60:63], v[178:181], v[146:149], v[60:63]
	v_mfma_f32_16x16x32_bf16 v[56:59], v[178:181], v[150:153], v[56:59]
	v_mfma_f32_16x16x32_bf16 v[52:55], v[178:181], v[154:157], v[52:55]
	v_mfma_f32_16x16x32_bf16 v[48:51], v[178:181], v[162:165], v[48:51]
	s_waitcnt lgkmcnt(2)
	v_mfma_f32_16x16x32_bf16 v[40:43], v[182:185], v[146:149], v[40:43]
	v_mfma_f32_16x16x32_bf16 v[44:47], v[182:185], v[150:153], v[44:47]
	v_mfma_f32_16x16x32_bf16 v[32:35], v[182:185], v[154:157], v[32:35]
	v_mfma_f32_16x16x32_bf16 v[36:39], v[182:185], v[162:165], v[36:39]
	s_waitcnt lgkmcnt(1)
	v_mfma_f32_16x16x32_bf16 v[24:27], v[186:189], v[146:149], v[24:27]
	v_mfma_f32_16x16x32_bf16 v[28:31], v[186:189], v[150:153], v[28:31]
	v_mfma_f32_16x16x32_bf16 v[16:19], v[186:189], v[154:157], v[16:19]
	v_mfma_f32_16x16x32_bf16 v[20:23], v[186:189], v[162:165], v[20:23]
	s_waitcnt lgkmcnt(0)
	v_mfma_f32_16x16x32_bf16 v[8:11], v[190:193], v[146:149], v[8:11]
	v_mfma_f32_16x16x32_bf16 v[12:15], v[190:193], v[150:153], v[12:15]
	v_mfma_f32_16x16x32_bf16 v[0:3], v[190:193], v[154:157], v[0:3]
	v_mfma_f32_16x16x32_bf16 v[4:7], v[190:193], v[162:165], v[4:7]
	s_add_i32 s8, s8, 32
	s_cmpk_lg_i32 s8, 0x400
	s_cbranch_scc0 .LBB0_208
	s_branch .Lffn8_adv
; #define MFMA(a, b, c) __builtin_amdgcn_mfma_f32_16x16x32_bf16((a), (b), (c), 0, 0, 0)
; #define ADV() { ga += 32; gb += 32; ck += 32; if (ck == K) { ck = 0; citem += gridDim.x; const int ci_ = citem < total ? citem : total - 1; SETPTR(ci_) } }
; #define WAITSTEP() { if (a2) WAITV(4); else WAITV(3); }
;     ...
;     for (int kt = 0; kt < nk; ++kt) {
;       if (VAR != 1) { const char* base = lds + scur; bf16x8 a[MI], b[4];
; #pragma unroll
;         for (int i = 0; i < 4; ++i) b[i] = *(const bf16x8*)(base + boff + i * 1024);
; #pragma unroll
;         for (int i = 0; i < MI; ++i) a[i] = *(const bf16x8*)(base + aoff + i * 1024);
; #pragma unroll
;         for (int i = 0; i < MI; ++i)
; #pragma unroll
;           for (int j = 0; j < 4; ++j) acc[i][j] = MFMA(a[i], b[j], acc[i][j]);
;         if (VAR != 2) GLDS(snext)
;     ...
;         if (MI == 8) {
;           __builtin_amdgcn_sched_group_barrier(0x100, MI + 4, 0);
; #pragma unroll
;           for (int g = 0; g < 4; ++g) { __builtin_amdgcn_sched_group_barrier(0x008, 7, 0); __builtin_amdgcn_sched_group_barrier(0x010, 1, 0); }
;           __builtin_amdgcn_sched_group_barrier(0x008, 4, 0);
;         } else if (MI == 6) {
;           __builtin_amdgcn_sched_group_barrier(0x100, MI + 4, 0);
; #pragma unroll
;           for (int g = 0; g < 4; ++g) { __builtin_amdgcn_sched_group_barrier(0x008, 5, 0); __builtin_amdgcn_sched_group_barrier(0x010, 1, 0); }
;           __builtin_amdgcn_sched_group_barrier(0x008, 4, 0);
;         }
;     ...
;       }
;       ADV()
;       if (VAR == 2) {} else WAITSTEP()
;       __builtin_amdgcn_s_barrier();
;       scur = (scur == 2 * STAGE) ? 0 : scur + STAGE;
;       snext = (snext == 2 * STAGE) ? 0 : snext + STAGE;
.Lffn8_hi:
	s_add_i32 s62, s4, 0
	v_add3_u32 v140, s62, v143, v144
	v_add3_u32 v128, s62, v145, v144
	ds_read_b128 v[158:161], v140
	ds_read_b128 v[146:149], v128 offset:16384
	ds_read_b128 v[150:153], v128 offset:17408
	ds_read_b128 v[154:157], v128 offset:18432
	ds_read_b128 v[162:165], v128 offset:19456
	ds_read_b128 v[166:169], v140 offset:1024
	ds_read_b128 v[170:173], v140 offset:2048
	ds_read_b128 v[174:177], v140 offset:3072
	ds_read_b128 v[178:181], v140 offset:4096
	ds_read_b128 v[182:185], v140 offset:5120
	ds_read_b128 v[186:189], v140 offset:6144
	ds_read_b128 v[190:193], v140 offset:7168
	s_waitcnt lgkmcnt(10)
	v_mfma_f32_16x16x32_bf16 v[124:127], v[158:161], v[146:149], v[124:127]
	s_waitcnt lgkmcnt(9)
	v_mfma_f32_16x16x32_bf16 v[120:123], v[158:161], v[150:153], v[120:123]
	s_waitcnt lgkmcnt(8)
	v_mfma_f32_16x16x32_bf16 v[116:119], v[158:161], v[154:157], v[116:119]
	s_waitcnt lgkmcnt(7)
	v_mfma_f32_16x16x32_bf16 v[112:115], v[158:161], v[162:165], v[112:115]
	s_waitcnt lgkmcnt(6)
	v_mfma_f32_16x16x32_bf16 v[108:111], v[166:169], v[146:149], v[108:111]
	v_mfma_f32_16x16x32_bf16 v[104:107], v[166:169], v[150:153], v[104:107]
	v_mfma_f32_16x16x32_bf16 v[100:103], v[166:169], v[154:157], v[100:103]
	v_mfma_f32_16x16x32_bf16 v[96:99], v[166:169], v[162:165], v[96:99]
	s_waitcnt lgkmcnt(5)
	v_mfma_f32_16x16x32_bf16 v[92:95], v[170:173], v[146:149], v[92:95]
	v_mfma_f32_16x16x32_bf16 v[88:91], v[170:173], v[150:153], v[88:91]
	v_mfma_f32_16x16x32_bf16 v[84:87], v[170:173], v[154:157], v[84:87]
	v_mfma_f32_16x16x32_bf16 v[80:83], v[170:173], v[162:165], v[80:83]
	s_waitcnt lgkmcnt(4)
	v_mfma_f32_16x16x32_bf16 v[76:79], v[174:177], v[146:149], v[76:79]
	v_mfma_f32_16x16x32_bf16 v[72:75], v[174:177], v[150:153], v[72:75]
	v_mfma_f32_16x16x32_bf16 v[68:71], v[174:177], v[154:157], v[68:71]
	v_mfma_f32_16x16x32_bf16 v[64:67], v[174:177], v[162:165], v[64:67]
	s_waitcnt lgkmcnt(3)
	v_mfma_f32_16x16x32_bf16 v[60:63], v[178:181], v[146:149], v[60:63]
	s_add_i32 s62, s5, s100
	s_mov_b32 m0, s62
	v_lshl_add_u64 v[194:195], v[136:137], 0, s[50:51]
	v_lshl_add_u64 v[196:197], v[138:139], 0, s[50:51]
	v_mfma_f32_16x16x32_bf16 v[56:59], v[178:181], v[150:153], v[56:59]
	v_mfma_f32_16x16x32_bf16 v[52:55], v[178:181], v[154:157], v[52:55]
	global_load_lds_dwordx4 v[136:137], off
	s_add_i32 m0, s62, 0x2000
	v_mfma_f32_16x16x32_bf16 v[48:51], v[178:181], v[162:165], v[48:51]
	s_waitcnt lgkmcnt(2)
	v_mfma_f32_16x16x32_bf16 v[40:43], v[182:185], v[146:149], v[40:43]
	v_mfma_f32_16x16x32_bf16 v[44:47], v[182:185], v[150:153], v[44:47]
	v_mfma_f32_16x16x32_bf16 v[32:35], v[182:185], v[154:157], v[32:35]
	global_load_lds_dwordx4 v[194:195], off
	s_add_i32 m0, s62, 0x4000
	v_mfma_f32_16x16x32_bf16 v[36:39], v[182:185], v[162:165], v[36:39]
	s_waitcnt lgkmcnt(1)
	v_mfma_f32_16x16x32_bf16 v[24:27], v[186:189], v[146:149], v[24:27]
	v_mfma_f32_16x16x32_bf16 v[28:31], v[186:189], v[150:153], v[28:31]
	v_mfma_f32_16x16x32_bf16 v[16:19], v[186:189], v[154:157], v[16:19]
	global_load_lds_dwordx4 v[138:139], off
	s_add_i32 m0, s62, 0x6000
	v_mfma_f32_16x16x32_bf16 v[20:23], v[186:189], v[162:165], v[20:23]
	s_waitcnt lgkmcnt(0)
	v_mfma_f32_16x16x32_bf16 v[8:11], v[190:193], v[146:149], v[8:11]
	v_mfma_f32_16x16x32_bf16 v[12:15], v[190:193], v[150:153], v[12:15]
	v_mfma_f32_16x16x32_bf16 v[0:3], v[190:193], v[154:157], v[0:3]
	global_load_lds_dwordx4 v[196:197], off
	v_mfma_f32_16x16x32_bf16 v[4:7], v[190:193], v[162:165], v[4:7]
	s_add_i32 s8, s8, 32
	s_cmpk_lg_i32 s8, 0x400
	s_cbranch_scc0 .LBB0_208
.Lffn8_adv:
	v_lshl_add_u64 v[136:137], v[136:137], 0, 64
	v_lshl_add_u64 v[138:139], v[138:139], 0, 64
	s_branch .LBB0_209

; __device__ __forceinline__ void phase_dif_attn(const Params& p, char* lds) {
;     ...
;     f32x4 oacc[2][8];
; #pragma unroll
;     for (int mi = 0; mi < 2; ++mi)
; #pragma unroll
;       for (int dv = 0; dv < 8; ++dv) oacc[mi][dv] = f32x4{0.f, 0.f, 0.f, 0.f};
;     float mrun[2] = {-1e30f, -1e30f}, lrun[2] = {0.f, 0.f};
;     bf16x8 rk[1], rv[2];
;     auto krow_of = [&](int kt) { return kt < 4 ? TL + b * 256 + kt * 64 : b * 8192 + (kt - 4) * 64; };
;     auto gload = [&](int kt) {
;       const int kr = krow_of(kt);
; #pragma unroll
;       for (int i = 0; i < 1; ++i) { const int id = tid; rk[i] = *(const bf16x8*)(Kn + (size_t)(kr + (id >> 3)) * 1024 + hm * 64 + (id & 7) * 8); }
;       const u16* vb = VT + ((size_t)(kr >> 6) * 1024 + hp * 128) * 64;
; #pragma unroll
;       for (int i = 0; i < 2; ++i) { const int id = tid + 512 * i; rv[i] = *(const bf16x8*)(vb + (size_t)id * 8); }
;     };
;     auto lwrite = [&](int buf) {
;       char* kb = lds + buf * BUFB; char* vbuf = kb + KB;
; #pragma unroll
;       for (int i = 0; i < 1; ++i) { const int id = tid, key = id >> 3, c = id & 7; *(bf16x8*)(kb + (c >> 2) * 4096 + key * 64 + (c & 3) * 16) = rk[i]; }
; #pragma unroll
;       for (int i = 0; i < 2; ++i) { const int id = tid + 512 * i, dv = id >> 3, c = id & 7; *(bf16x8*)(vbuf + dv * 144 + c * 16) = rv[i]; }
;     };
;     gload(0); lwrite(0);
;     __syncthreads();
;     for (int kt = 0; kt < ntile; ++kt) {
;       const char* kb = lds + (kt & 1) * BUFB; const char* vbuf = kb + KB;
;       if (kt + 1 < ntile) gload(kt + 1);
;       f32x4 st[2][4];
; #pragma unroll
;       for (int mi = 0; mi < 2; ++mi)
; #pragma unroll
;         for (int n = 0; n < 4; ++n) st[mi][n] = f32x4{0.f, 0.f, 0.f, 0.f};
; #pragma unroll
;       for (int kk = 0; kk < 2; ++kk)
; #pragma unroll
;         for (int n = 0; n < 4; ++n) {
;           bf16x8 ka = *(const bf16x8*)(kb + kk * 4096 + (n * 16 + l15) * 64 + quad * 16);
; #pragma unroll
;           for (int mi = 0; mi < 2; ++mi) st[mi][n] = MFMA(ka, qf[mi][kk], st[mi][n]);
;         }
;       bf16x8 pb[2][2];
; #pragma unroll
;       for (int mi = 0; mi < 2; ++mi) {
;         float mx = -1e30f;
; #pragma unroll
;         for (int n = 0; n < 4; ++n)
; #pragma unroll
;           for (int j = 0; j < 4; ++j) mx = fmaxf(mx, st[mi][n][j]);
;         mx = fmaxf(mx, __shfl_xor(mx, 16)); mx = fmaxf(mx, __shfl_xor(mx, 32));
.LBB0_500:
	s_and_b32 s0, s1, 15
	v_add_u32_e32 v144, s6, v131
	s_lshl_b32 s86, s0, 7
	v_ashrrev_i32_e32 v145, 31, v144
	v_lshl_add_u64 v[0:1], v[132:133], 0, s[86:87]
	v_lshlrev_b64 v[2:3], 11, v[144:145]
	v_add_u32_e32 v142, 16, v144
	v_lshl_add_u64 v[2:3], v[0:1], 0, v[2:3]
	v_ashrrev_i32_e32 v143, 31, v142
	global_load_dwordx4 v[72:75], v[2:3], off
	global_load_dwordx4 v[64:67], v[2:3], off offset:64
	v_lshlrev_b64 v[2:3], 11, v[142:143]
	v_lshl_add_u64 v[0:1], v[0:1], 0, v[2:3]
	global_load_dwordx4 v[76:79], v[0:1], off
	global_load_dwordx4 v[68:71], v[0:1], off offset:64
	v_add_u32_e32 v0, s4, v127
	v_ashrrev_i32_e32 v1, 31, v0
	v_readlane_b32 s6, v254, 26
	v_lshlrev_b64 v[0:1], 11, v[0:1]
	v_readlane_b32 s7, v254, 27
	s_lshl_b32 s1, s1, 13
	s_and_b32 s1, s1, 0x1c000
	v_lshl_add_u64 v[0:1], s[6:7], 0, v[0:1]
	s_ashr_i32 s6, s4, 6
	s_ashr_i32 s7, s6, 31
	s_lshl_b64 s[6:7], s[6:7], 17
	v_readlane_b32 s8, v254, 28
	v_readlane_b32 s9, v254, 29
	s_add_u32 s4, s8, s6
	s_addc_u32 s7, s9, s7
	v_lshl_add_u64 v[0:1], v[0:1], 0, s[86:87]
	s_add_u32 s6, s4, s1
	v_lshl_add_u64 v[0:1], v[0:1], 0, v[128:129]
	s_addc_u32 s7, s7, 0
	global_load_dwordx4 v[0:3], v[0:1], off
	v_lshl_add_u64 v[4:5], s[6:7], 0, v[134:135]
	global_load_dwordx4 v[4:7], v[4:5], off
	v_lshl_add_u64 v[8:9], s[6:7], 0, v[136:137]
	global_load_dwordx4 v[8:11], v[8:9], off
	s_add_u32 s1, s8, s1
	v_lshl_add_u64 v[146:147], v[138:139], 0, s[86:87]
	s_addc_u32 s4, s9, 0
	s_add_i32 s5, s5, 1
	s_mov_b32 s6, 0
	v_mov_b32_e32 v164, 0
	v_mov_b32_e32 v162, 0xf149f2ca
	s_mov_b32 s7, 64
	v_mov_b32_e32 v163, 0xf149f2ca
	v_mov_b32_e32 v165, 0
	s_waitcnt vmcnt(2)
	ds_write_b128 v159, v[0:3]
	s_waitcnt vmcnt(1)
	ds_write_b128 v160, v[4:7] offset:8192
	s_waitcnt vmcnt(0)
	ds_write_b128 v161, v[8:11] offset:8192
	v_mov_b32_e32 v2, v129
	v_mov_b32_e32 v3, v129
	v_mov_b32_e32 v0, v129
	v_mov_b32_e32 v1, v129
	v_mov_b64_e32 v[10:11], v[2:3]
	v_mov_b64_e32 v[18:19], v[2:3]
	v_mov_b64_e32 v[26:27], v[2:3]
	v_mov_b64_e32 v[34:35], v[2:3]
	v_mov_b64_e32 v[42:43], v[2:3]
	v_mov_b64_e32 v[54:55], v[2:3]
	v_mov_b64_e32 v[58:59], v[2:3]
	v_mov_b64_e32 v[6:7], v[2:3]
	v_mov_b64_e32 v[14:15], v[2:3]
	v_mov_b64_e32 v[22:23], v[2:3]
	v_mov_b64_e32 v[30:31], v[2:3]
	v_mov_b64_e32 v[38:39], v[2:3]
	v_mov_b64_e32 v[46:47], v[2:3]
	v_mov_b64_e32 v[50:51], v[2:3]
	v_mov_b64_e32 v[62:63], v[2:3]
	v_mov_b64_e32 v[8:9], v[0:1]
	v_mov_b64_e32 v[16:17], v[0:1]
	v_mov_b64_e32 v[24:25], v[0:1]
	v_mov_b64_e32 v[32:33], v[0:1]
	v_mov_b64_e32 v[40:41], v[0:1]
	v_mov_b64_e32 v[52:53], v[0:1]
	v_mov_b64_e32 v[56:57], v[0:1]
	v_mov_b64_e32 v[4:5], v[0:1]
	v_mov_b64_e32 v[12:13], v[0:1]
	v_mov_b64_e32 v[20:21], v[0:1]
	v_mov_b64_e32 v[28:29], v[0:1]
	v_mov_b64_e32 v[36:37], v[0:1]
	v_mov_b64_e32 v[44:45], v[0:1]
	v_mov_b64_e32 v[48:49], v[0:1]
	v_mov_b64_e32 v[60:61], v[0:1]
	v_mov_b32_e32 v240, 0
	v_mov_b32_e32 v241, 0
	v_mov_b32_e32 v242, 0
	v_mov_b32_e32 v243, 0
	v_mov_b32_e32 v244, 0
	v_mov_b32_e32 v245, 0
	v_mov_b32_e32 v246, 0
	v_mov_b32_e32 v247, 0
	s_mov_b32 s100, 0xf149f2ca
	s_mov_b32 s101, 0xf149f2ca
	s_waitcnt lgkmcnt(0)
	s_barrier
.LBB0_501:
	s_bitcmp1_b32 s6, 0
	s_cselect_b32 s8, 0x6800, 0
	s_add_i32 s8, s8, 0
	v_add3_u32 v148, s8, v126, v156
	v_add3_u32 v198, s8, v125, v124
	ds_read_b128 v[178:181], v148
	ds_read_b128 v[182:185], v148 offset:1024
	ds_read_b128 v[186:189], v148 offset:2048
	ds_read_b128 v[190:193], v148 offset:3072
	ds_read_b128 v[194:197], v148 offset:4096
	ds_read_b128 v[228:231], v148 offset:5120
	ds_read_b128 v[232:235], v148 offset:6144
	ds_read_b128 v[236:239], v148 offset:7168
	s_cmp_lt_u32 s6, 3
	s_cselect_b32 s9, 8, 13
	s_cselect_b32 s62, s77, 0xffffff00
	s_lshl_b32 s9, s3, s9
	s_add_i32 s62, s62, s9
	s_add_i32 s9, s7, s62
	s_ashr_i32 s62, s9, 6
	s_ashr_i32 s63, s62, 31
	v_add_u32_e32 v80, s9, v127
	s_lshl_b64 s[62:63], s[62:63], 17
	v_ashrrev_i32_e32 v81, 31, v80
	s_add_u32 s62, s1, s62
	v_lshlrev_b64 v[80:81], 11, v[80:81]
	s_addc_u32 s63, s4, s63
	v_lshl_add_u64 v[80:81], v[146:147], 0, v[80:81]
	v_lshl_add_u64 v[84:85], s[62:63], 0, v[134:135]
	v_lshl_add_u64 v[88:89], s[62:63], 0, v[136:137]
	global_load_dwordx4 v[80:83], v[80:81], off
	global_load_dwordx4 v[84:87], v[84:85], off
	global_load_dwordx4 v[88:91], v[88:89], off
	s_waitcnt lgkmcnt(7)
	v_mfma_f32_16x16x32_bf16 v[120:123], v[178:181], v[72:75], v[240:243]
	v_mfma_f32_16x16x32_bf16 v[104:107], v[178:181], v[76:79], v[244:247]
	s_waitcnt lgkmcnt(6)
	v_mfma_f32_16x16x32_bf16 v[116:119], v[182:185], v[72:75], v[240:243]
	v_mfma_f32_16x16x32_bf16 v[100:103], v[182:185], v[76:79], v[244:247]
	s_waitcnt lgkmcnt(5)
	v_mfma_f32_16x16x32_bf16 v[112:115], v[186:189], v[72:75], v[240:243]
	v_mfma_f32_16x16x32_bf16 v[96:99], v[186:189], v[76:79], v[244:247]
	s_waitcnt lgkmcnt(4)
	v_mfma_f32_16x16x32_bf16 v[108:111], v[190:193], v[72:75], v[240:243]
	v_mfma_f32_16x16x32_bf16 v[92:95], v[190:193], v[76:79], v[244:247]
	s_waitcnt lgkmcnt(3)
	v_mfma_f32_16x16x32_bf16 v[120:123], v[194:197], v[64:67], v[120:123]
	v_mfma_f32_16x16x32_bf16 v[104:107], v[194:197], v[68:71], v[104:107]
	s_waitcnt lgkmcnt(2)
	v_mfma_f32_16x16x32_bf16 v[116:119], v[228:231], v[64:67], v[116:119]
	v_mfma_f32_16x16x32_bf16 v[100:103], v[228:231], v[68:71], v[100:103]
	s_waitcnt lgkmcnt(1)
	v_mfma_f32_16x16x32_bf16 v[112:115], v[232:235], v[64:67], v[112:115]
	v_mfma_f32_16x16x32_bf16 v[96:99], v[232:235], v[68:71], v[96:99]
	s_waitcnt lgkmcnt(0)
	v_mfma_f32_16x16x32_bf16 v[108:111], v[236:239], v[64:67], v[108:111]
	v_mfma_f32_16x16x32_bf16 v[92:95], v[236:239], v[68:71], v[92:95]
	ds_read_b64 v[178:179], v198 offset:8192
	ds_read_b64 v[180:181], v198 offset:8224
	ds_read_b64 v[182:183], v198 offset:10496
	ds_read_b64 v[184:185], v198 offset:10528
	ds_read_b64 v[186:187], v198 offset:12800
	ds_read_b64 v[188:189], v198 offset:12832
	ds_read_b64 v[190:191], v198 offset:15104
	ds_read_b64 v[192:193], v198 offset:15136
	ds_read_b64 v[194:195], v198 offset:17408
	ds_read_b64 v[196:197], v198 offset:17440
	ds_read_b64 v[228:229], v198 offset:19712
	ds_read_b64 v[230:231], v198 offset:19744
	ds_read_b64 v[232:233], v198 offset:22016
	ds_read_b64 v[234:235], v198 offset:22048
	v_max3_f32 v148, v120, s21, v121
	v_max3_f32 v148, v148, v122, v123
	v_max3_f32 v148, v148, v116, v117
	v_max3_f32 v148, v148, v118, v119
	v_max3_f32 v148, v148, v112, v113
	v_max3_f32 v148, v148, v114, v115
	v_max3_f32 v148, v148, v108, v109
	v_max3_f32 v148, v148, v110, v111
	v_max3_f32 v150, v104, s21, v105
	v_max3_f32 v150, v150, v106, v107
	v_max3_f32 v150, v150, v100, v101
	v_max3_f32 v150, v150, v102, v103
	v_max3_f32 v150, v150, v96, v97
	v_max3_f32 v150, v150, v98, v99
	v_max3_f32 v150, v150, v92, v93
	v_max3_f32 v150, v150, v94, v95
	v_cmp_ge_f32_e32 vcc, s100, v148
	s_nop 0
	s_cmp_eq_u64 vcc, exec
	s_cbranch_scc0 .Lattn_slow0
; __device__ __forceinline__ unsigned cvtpk(float lo, float hi) { f32x2_t v = {lo, hi}; bf16x2_t r = __builtin_convertvector(v, bf16x2_t); return *reinterpret_cast<unsigned*>(&r); }
; #define MFMA(a, b, c) __builtin_amdgcn_mfma_f32_16x16x32_bf16((a), (b), (c), 0, 0, 0)
; __device__ __forceinline__ void phase_dif_attn(const Params& p, char* lds) {
;     ...
;         float rsum = 0.f;
; #pragma unroll
;         for (int n = 0; n < 4; ++n)
; #pragma unroll
;           for (int j = 0; j < 4; ++j) { float pv = __builtin_amdgcn_exp2f(st[mi][n][j] - mnew); st[mi][n][j] = pv; rsum += pv; }
;         lrun[mi] = lrun[mi] * alpha + rsum;
; #pragma unroll
;         for (int ks = 0; ks < 2; ++ks) {
;           u32x4 v = {cvtpk(st[mi][2 * ks][0], st[mi][2 * ks][1]), cvtpk(st[mi][2 * ks][2], st[mi][2 * ks][3]),
;                      cvtpk(st[mi][2 * ks + 1][0], st[mi][2 * ks + 1][1]), cvtpk(st[mi][2 * ks + 1][2], st[mi][2 * ks + 1][3])};
;           pb[mi][ks] = *reinterpret_cast<bf16x8*>(&v);
;         }
;       }
; #pragma unroll
;       for (int dv = 0; dv < 8; ++dv)
; #pragma unroll
;         for (int ks = 0; ks < 2; ++ks) {
;           const char* vp = vbuf + (dv * 16 + l15) * 144 + (ks * 32 + quad * 4) * 2;
;           bf16x4 lo = *(const bf16x4*)vp, hi = *(const bf16x4*)(vp + 32);
;           bf16x8 va = {lo[0], lo[1], lo[2], lo[3], hi[0], hi[1], hi[2], hi[3]};
; #pragma unroll
;           for (int mi = 0; mi < 2; ++mi) oacc[mi][dv] = MFMA(va, pb[mi][ks], oacc[mi][dv]);
;           if (ks == 1 && (dv & 1)) __builtin_amdgcn_sched_barrier(0);
;         }
;       if (kt + 1 < ntile) lwrite((kt + 1) & 1);
;       __syncthreads();
.Lattn_back0:
	v_cmp_ge_f32_e32 vcc, s101, v150
	s_nop 0
	s_cmp_eq_u64 vcc, exec
	s_cbranch_scc0 .Lattn_slow1
.Lattn_back1:
	v_exp_f32_e32 v120, v120
	v_exp_f32_e32 v104, v104
	v_exp_f32_e32 v121, v121
	v_exp_f32_e32 v105, v105
	v_exp_f32_e32 v122, v122
	v_exp_f32_e32 v106, v106
	v_exp_f32_e32 v123, v123
	v_exp_f32_e32 v107, v107
	v_exp_f32_e32 v116, v116
	v_exp_f32_e32 v100, v100
	v_exp_f32_e32 v117, v117
	v_exp_f32_e32 v101, v101
	v_exp_f32_e32 v118, v118
	v_exp_f32_e32 v102, v102
	v_exp_f32_e32 v119, v119
	v_exp_f32_e32 v103, v103
	v_add_f32_e32 v165, v165, v120
	v_add_f32_e32 v164, v164, v104
	v_add_f32_e32 v165, v165, v121
	v_add_f32_e32 v164, v164, v105
	v_add_f32_e32 v165, v165, v122
	v_add_f32_e32 v164, v164, v106
	v_add_f32_e32 v165, v165, v123
	v_add_f32_e32 v164, v164, v107
	v_add_f32_e32 v165, v165, v116
	v_add_f32_e32 v164, v164, v100
	v_add_f32_e32 v165, v165, v117
	v_add_f32_e32 v164, v164, v101
	v_add_f32_e32 v165, v165, v118
	v_add_f32_e32 v164, v164, v102
	v_add_f32_e32 v165, v165, v119
	v_add_f32_e32 v164, v164, v103
	v_cvt_pk_bf16_f32 v166, v120, v121
	v_cvt_pk_bf16_f32 v167, v122, v123
	v_cvt_pk_bf16_f32 v168, v116, v117
	v_cvt_pk_bf16_f32 v169, v118, v119
	v_cvt_pk_bf16_f32 v170, v104, v105
	v_cvt_pk_bf16_f32 v171, v106, v107
	v_cvt_pk_bf16_f32 v172, v100, v101
	v_cvt_pk_bf16_f32 v173, v102, v103
	v_exp_f32_e32 v112, v112
	v_exp_f32_e32 v96, v96
	s_waitcnt lgkmcnt(12)
	v_mfma_f32_16x16x32_bf16 v[60:63], v[178:181], v[166:169], v[60:63]
	v_exp_f32_e32 v113, v113
	v_exp_f32_e32 v97, v97
	v_exp_f32_e32 v114, v114
	v_mfma_f32_16x16x32_bf16 v[56:59], v[178:181], v[170:173], v[56:59]
	v_exp_f32_e32 v98, v98
	v_exp_f32_e32 v115, v115
	ds_read_b64 v[236:237], v198 offset:24320
	ds_read_b64 v[238:239], v198 offset:24352
	s_waitcnt lgkmcnt(12)
	v_mfma_f32_16x16x32_bf16 v[48:51], v[182:185], v[166:169], v[48:51]
	v_exp_f32_e32 v99, v99
	v_exp_f32_e32 v108, v108
	v_exp_f32_e32 v92, v92
	v_mfma_f32_16x16x32_bf16 v[52:55], v[182:185], v[170:173], v[52:55]
	v_exp_f32_e32 v109, v109
	v_exp_f32_e32 v93, v93
	ds_read_b64 v[178:179], v198 offset:8256
	ds_read_b64 v[180:181], v198 offset:8288
	s_waitcnt lgkmcnt(12)
	v_mfma_f32_16x16x32_bf16 v[44:47], v[186:189], v[166:169], v[44:47]
	v_exp_f32_e32 v110, v110
	v_exp_f32_e32 v94, v94
	v_exp_f32_e32 v111, v111
	v_mfma_f32_16x16x32_bf16 v[40:43], v[186:189], v[170:173], v[40:43]
	v_exp_f32_e32 v95, v95
	v_add_f32_e32 v165, v165, v112
	ds_read_b64 v[182:183], v198 offset:10560
	ds_read_b64 v[184:185], v198 offset:10592
	s_waitcnt lgkmcnt(12)
	v_mfma_f32_16x16x32_bf16 v[36:39], v[190:193], v[166:169], v[36:39]
	v_add_f32_e32 v164, v164, v96
	v_add_f32_e32 v165, v165, v113
	v_add_f32_e32 v164, v164, v97
	v_mfma_f32_16x16x32_bf16 v[32:35], v[190:193], v[170:173], v[32:35]
	v_add_f32_e32 v165, v165, v114
	v_add_f32_e32 v164, v164, v98
	ds_read_b64 v[186:187], v198 offset:12864
	ds_read_b64 v[188:189], v198 offset:12896
	s_waitcnt lgkmcnt(12)
	v_mfma_f32_16x16x32_bf16 v[28:31], v[194:197], v[166:169], v[28:31]
	v_add_f32_e32 v165, v165, v115
	v_add_f32_e32 v164, v164, v99
	v_add_f32_e32 v165, v165, v108
	v_mfma_f32_16x16x32_bf16 v[24:27], v[194:197], v[170:173], v[24:27]
	v_add_f32_e32 v164, v164, v92
	v_add_f32_e32 v165, v165, v109
	ds_read_b64 v[190:191], v198 offset:15168
	ds_read_b64 v[192:193], v198 offset:15200
	s_waitcnt lgkmcnt(12)
	v_mfma_f32_16x16x32_bf16 v[20:23], v[228:231], v[166:169], v[20:23]
	v_add_f32_e32 v164, v164, v93
	v_add_f32_e32 v165, v165, v110
	v_add_f32_e32 v164, v164, v94
	v_mfma_f32_16x16x32_bf16 v[16:19], v[228:231], v[170:173], v[16:19]
	v_add_f32_e32 v165, v165, v111
	v_add_f32_e32 v164, v164, v95
	ds_read_b64 v[194:195], v198 offset:17472
	ds_read_b64 v[196:197], v198 offset:17504
	s_waitcnt lgkmcnt(12)
	v_mfma_f32_16x16x32_bf16 v[12:15], v[232:235], v[166:169], v[12:15]
	v_cvt_pk_bf16_f32 v174, v112, v113
	v_cvt_pk_bf16_f32 v175, v114, v115
	v_cvt_pk_bf16_f32 v176, v108, v109
	v_mfma_f32_16x16x32_bf16 v[8:11], v[232:235], v[170:173], v[8:11]
	v_cvt_pk_bf16_f32 v177, v110, v111
	v_cvt_pk_bf16_f32 v248, v96, v97
	ds_read_b64 v[228:229], v198 offset:19776
	ds_read_b64 v[230:231], v198 offset:19808
	s_waitcnt lgkmcnt(12)
	v_mfma_f32_16x16x32_bf16 v[4:7], v[236:239], v[166:169], v[4:7]
	v_cvt_pk_bf16_f32 v249, v98, v99
	v_cvt_pk_bf16_f32 v250, v92, v93
	v_cvt_pk_bf16_f32 v251, v94, v95
	v_mfma_f32_16x16x32_bf16 v[0:3], v[236:239], v[170:173], v[0:3]
	ds_read_b64 v[232:233], v198 offset:22080
	ds_read_b64 v[234:235], v198 offset:22112
	s_add_i32 s6, s6, 1
	s_waitcnt lgkmcnt(12)
	v_mfma_f32_16x16x32_bf16 v[60:63], v[178:181], v[174:177], v[60:63]
	v_mfma_f32_16x16x32_bf16 v[56:59], v[178:181], v[248:251], v[56:59]
	ds_read_b64 v[236:237], v198 offset:24384
	ds_read_b64 v[238:239], v198 offset:24416
	s_waitcnt lgkmcnt(12)
	v_mfma_f32_16x16x32_bf16 v[48:51], v[182:185], v[174:177], v[48:51]
	v_mfma_f32_16x16x32_bf16 v[52:55], v[182:185], v[248:251], v[52:55]
	s_waitcnt lgkmcnt(10)
	v_mfma_f32_16x16x32_bf16 v[44:47], v[186:189], v[174:177], v[44:47]
	v_mfma_f32_16x16x32_bf16 v[40:43], v[186:189], v[248:251], v[40:43]
	s_bitcmp1_b32 s6, 0
	s_cselect_b32 s8, 0x6800, 0
	s_add_i32 s8, s8, 0
	v_add_u32_e32 v92, s8, v149
	v_add3_u32 v92, v92, v151, v152
	s_waitcnt vmcnt(2)
	ds_write_b128 v92, v[80:83]
	v_add3_u32 v80, s8, v153, v154
	s_add_i32 s7, s7, 64
	s_waitcnt vmcnt(1)
	ds_write_b128 v80, v[84:87] offset:8192
	v_add3_u32 v80, s8, v155, v154
	s_waitcnt vmcnt(0)
	ds_write_b128 v80, v[88:91] offset:8192
	s_waitcnt lgkmcnt(11)
	v_mfma_f32_16x16x32_bf16 v[36:39], v[190:193], v[174:177], v[36:39]
	v_mfma_f32_16x16x32_bf16 v[32:35], v[190:193], v[248:251], v[32:35]
	s_waitcnt lgkmcnt(9)
	v_mfma_f32_16x16x32_bf16 v[28:31], v[194:197], v[174:177], v[28:31]
	v_mfma_f32_16x16x32_bf16 v[24:27], v[194:197], v[248:251], v[24:27]
	s_waitcnt lgkmcnt(7)
	v_mfma_f32_16x16x32_bf16 v[20:23], v[228:231], v[174:177], v[20:23]
	v_mfma_f32_16x16x32_bf16 v[16:19], v[228:231], v[248:251], v[16:19]
	s_waitcnt lgkmcnt(5)
	v_mfma_f32_16x16x32_bf16 v[12:15], v[232:235], v[174:177], v[12:15]
	v_mfma_f32_16x16x32_bf16 v[8:11], v[232:235], v[248:251], v[8:11]
	s_waitcnt lgkmcnt(3)
	v_mfma_f32_16x16x32_bf16 v[4:7], v[236:239], v[174:177], v[4:7]
	v_mfma_f32_16x16x32_bf16 v[0:3], v[236:239], v[248:251], v[0:3]
	v_mov_b32_e32 v116, v165
	v_mov_b32_e32 v101, v164
	s_cmp_eq_u32 s5, s6
	s_waitcnt lgkmcnt(0)
	s_barrier
	s_cbranch_scc1 .LBB0_508
	v_mov_b32_e32 v164, v101
	v_mov_b32_e32 v165, v116
	s_branch .LBB0_501
; __device__ __forceinline__ void phase_dif_attn(const Params& p, char* lds) {
;     ...
;         float mnew = mrun[mi], alpha = 1.f;
;         if (!__all(mx - mrun[mi] <= 8.f)) {
;           mnew = fmaxf(mrun[mi], mx);
;           alpha = __builtin_amdgcn_exp2f(mrun[mi] - mnew);
;           mrun[mi] = mnew;
; #pragma unroll
;           for (int dv = 0; dv < 8; ++dv) oacc[mi][dv] *= alpha;
;         }
;         float rsum = 0.f;
; #pragma unroll
;         for (int n = 0; n < 4; ++n)
; #pragma unroll
;           for (int j = 0; j < 4; ++j) { float pv = __builtin_amdgcn_exp2f(st[mi][n][j] - mnew); st[mi][n][j] = pv; rsum += pv; }
;         lrun[mi] = lrun[mi] * alpha + rsum;
.Lattn_slow0:
	ds_bpermute_b32 v199, v157, v148
	s_waitcnt lgkmcnt(0)
	v_max_f32_e32 v148, v148, v199
	ds_bpermute_b32 v199, v158, v148
	s_waitcnt lgkmcnt(0)
	v_max_f32_e32 v148, v148, v199
	v_sub_f32_e32 v148, v148, v240
	v_max_f32_e32 v199, v163, v148
	v_sub_f32_e32 v206, v163, v199
	v_exp_f32_e32 v206, v206
	v_sub_f32_e64 v148, -v240, v199
	v_mov_b32_e32 v163, v199
	v_sub_f32_e32 v240, 0, v199
	v_mul_f32_e32 v165, v165, v206
	v_mov_b32_e32 v241, v240
	v_mov_b32_e32 v242, v240
	v_mov_b32_e32 v243, v240
	v_pk_mul_f32 v[60:61], v[60:61], v[206:207] op_sel_hi:[1,0]
	v_pk_mul_f32 v[62:63], v[62:63], v[206:207] op_sel_hi:[1,0]
	v_pk_mul_f32 v[48:49], v[48:49], v[206:207] op_sel_hi:[1,0]
	v_pk_mul_f32 v[50:51], v[50:51], v[206:207] op_sel_hi:[1,0]
	v_pk_mul_f32 v[44:45], v[44:45], v[206:207] op_sel_hi:[1,0]
	v_pk_mul_f32 v[46:47], v[46:47], v[206:207] op_sel_hi:[1,0]
	v_pk_mul_f32 v[36:37], v[36:37], v[206:207] op_sel_hi:[1,0]
	v_pk_mul_f32 v[38:39], v[38:39], v[206:207] op_sel_hi:[1,0]
	v_pk_mul_f32 v[28:29], v[28:29], v[206:207] op_sel_hi:[1,0]
	v_pk_mul_f32 v[30:31], v[30:31], v[206:207] op_sel_hi:[1,0]
	v_pk_mul_f32 v[20:21], v[20:21], v[206:207] op_sel_hi:[1,0]
	v_pk_mul_f32 v[22:23], v[22:23], v[206:207] op_sel_hi:[1,0]
	v_pk_mul_f32 v[12:13], v[12:13], v[206:207] op_sel_hi:[1,0]
	v_pk_mul_f32 v[14:15], v[14:15], v[206:207] op_sel_hi:[1,0]
	v_pk_mul_f32 v[4:5], v[4:5], v[206:207] op_sel_hi:[1,0]
	v_pk_mul_f32 v[6:7], v[6:7], v[206:207] op_sel_hi:[1,0]
	v_add_f32_e32 v120, v120, v148
	v_add_f32_e32 v121, v121, v148
	v_add_f32_e32 v122, v122, v148
	v_add_f32_e32 v123, v123, v148
	v_add_f32_e32 v116, v116, v148
	v_add_f32_e32 v117, v117, v148
	v_add_f32_e32 v118, v118, v148
	v_add_f32_e32 v119, v119, v148
	v_add_f32_e32 v112, v112, v148
	v_add_f32_e32 v113, v113, v148
	v_add_f32_e32 v114, v114, v148
	v_add_f32_e32 v115, v115, v148
	v_add_f32_e32 v108, v108, v148
	v_add_f32_e32 v109, v109, v148
	v_add_f32_e32 v110, v110, v148
	v_add_f32_e32 v111, v111, v148
	s_mov_b32 s100, s22
	s_branch .Lattn_back0
.Lattn_slow1:
	ds_bpermute_b32 v199, v157, v150
	s_waitcnt lgkmcnt(0)
	v_max_f32_e32 v150, v150, v199
	ds_bpermute_b32 v199, v158, v150
	s_waitcnt lgkmcnt(0)
	v_max_f32_e32 v150, v150, v199
	v_sub_f32_e32 v150, v150, v244
	v_max_f32_e32 v199, v162, v150
	v_sub_f32_e32 v206, v162, v199
	v_exp_f32_e32 v206, v206
	v_sub_f32_e64 v150, -v244, v199
	v_mov_b32_e32 v162, v199
	v_sub_f32_e32 v244, 0, v199
	v_mul_f32_e32 v164, v164, v206
	v_mov_b32_e32 v245, v244
	v_mov_b32_e32 v246, v244
	v_mov_b32_e32 v247, v244
	v_pk_mul_f32 v[56:57], v[56:57], v[206:207] op_sel_hi:[1,0]
	v_pk_mul_f32 v[58:59], v[58:59], v[206:207] op_sel_hi:[1,0]
	v_pk_mul_f32 v[52:53], v[52:53], v[206:207] op_sel_hi:[1,0]
	v_pk_mul_f32 v[54:55], v[54:55], v[206:207] op_sel_hi:[1,0]
	v_pk_mul_f32 v[40:41], v[40:41], v[206:207] op_sel_hi:[1,0]
	v_pk_mul_f32 v[42:43], v[42:43], v[206:207] op_sel_hi:[1,0]
	v_pk_mul_f32 v[32:33], v[32:33], v[206:207] op_sel_hi:[1,0]
	v_pk_mul_f32 v[34:35], v[34:35], v[206:207] op_sel_hi:[1,0]
	v_pk_mul_f32 v[24:25], v[24:25], v[206:207] op_sel_hi:[1,0]
	v_pk_mul_f32 v[26:27], v[26:27], v[206:207] op_sel_hi:[1,0]
	v_pk_mul_f32 v[16:17], v[16:17], v[206:207] op_sel_hi:[1,0]
	v_pk_mul_f32 v[18:19], v[18:19], v[206:207] op_sel_hi:[1,0]
	v_pk_mul_f32 v[8:9], v[8:9], v[206:207] op_sel_hi:[1,0]
	v_pk_mul_f32 v[10:11], v[10:11], v[206:207] op_sel_hi:[1,0]
	v_pk_mul_f32 v[0:1], v[0:1], v[206:207] op_sel_hi:[1,0]
	v_pk_mul_f32 v[2:3], v[2:3], v[206:207] op_sel_hi:[1,0]
	v_add_f32_e32 v104, v104, v150
	v_add_f32_e32 v105, v105, v150
	v_add_f32_e32 v106, v106, v150
	v_add_f32_e32 v107, v107, v150
	v_add_f32_e32 v100, v100, v150
	v_add_f32_e32 v101, v101, v150
	v_add_f32_e32 v102, v102, v150
	v_add_f32_e32 v103, v103, v150
	v_add_f32_e32 v96, v96, v150
	v_add_f32_e32 v97, v97, v150
	v_add_f32_e32 v98, v98, v150
	v_add_f32_e32 v99, v99, v150
	v_add_f32_e32 v92, v92, v150
	v_add_f32_e32 v93, v93, v150
	v_add_f32_e32 v94, v94, v150
	v_add_f32_e32 v95, v95, v150
	s_mov_b32 s101, s22
	s_branch .Lattn_back1

; __global__ void __launch_bounds__(512, 2) mega(Params p) {
;   cg::grid_group grid = cg::this_grid();
;   unsigned* gbar = (unsigned*)(p.ws + O_GBAR);
;   char* smem = g_smem;
;     ...
;   if (threadIdx.x < 32) ((unsigned*)(g_smem + BAR_OFF))[threadIdx.x] = 0u;
;   __syncthreads();
	.amdhsa_kernel _Z4mega6Params
		.amdhsa_group_segment_fixed_size 0
		.amdhsa_private_segment_fixed_size 0
		.amdhsa_kernarg_size 456
		.amdhsa_user_sgpr_count 2
		.amdhsa_user_sgpr_dispatch_ptr 0
		.amdhsa_user_sgpr_queue_ptr 0
		.amdhsa_user_sgpr_kernarg_segment_ptr 1
		.amdhsa_user_sgpr_dispatch_id 0
		.amdhsa_user_sgpr_kernarg_preload_length 0
		.amdhsa_user_sgpr_kernarg_preload_offset 0
		.amdhsa_user_sgpr_private_segment_size 0
		.amdhsa_uses_dynamic_stack 0
		.amdhsa_enable_private_segment 0
		.amdhsa_system_sgpr_workgroup_id_x 1
		.amdhsa_system_sgpr_workgroup_id_y 0
		.amdhsa_system_sgpr_workgroup_id_z 0
		.amdhsa_system_sgpr_workgroup_info 0
		.amdhsa_system_vgpr_workitem_id 2
		.amdhsa_next_free_vgpr 256
		.amdhsa_next_free_sgpr 102
		.amdhsa_accum_offset 256
		.amdhsa_reserve_vcc 1
		.amdhsa_float_round_mode_32 0
		.amdhsa_float_round_mode_16_64 0
		.amdhsa_float_denorm_mode_32 3
		.amdhsa_float_denorm_mode_16_64 3
		.amdhsa_dx10_clamp 1
		.amdhsa_ieee_mode 1
		.amdhsa_fp16_overflow 0
		.amdhsa_tg_split 0
		.amdhsa_exception_fp_ieee_invalid_op 0
		.amdhsa_exception_fp_denorm_src 0
		.amdhsa_exception_fp_ieee_div_zero 0
		.amdhsa_exception_fp_ieee_overflow 0
		.amdhsa_exception_fp_ieee_underflow 0
		.amdhsa_exception_fp_ieee_inexact 0
		.amdhsa_exception_int_div_zero 0
	.end_amdhsa_kernel

; __global__ void __launch_bounds__(512, 2) mega(Params p) {
;   cg::grid_group grid = cg::this_grid();
;   unsigned* gbar = (unsigned*)(p.ws + O_GBAR);
;   char* smem = g_smem;
;     ...
;   if (threadIdx.x < 32) ((unsigned*)(g_smem + BAR_OFF))[threadIdx.x] = 0u;
;   __syncthreads();
amdhsa.kernels:
  - .agpr_count:     0
    .args:
      - .offset:         0
        .size:           200
        .value_kind:     by_value
      - .offset:         200
        .size:           4
        .value_kind:     hidden_block_count_x
      - .offset:         204
        .size:           4
        .value_kind:     hidden_block_count_y
      - .offset:         208
        .size:           4
        .value_kind:     hidden_block_count_z
      - .offset:         212
        .size:           2
        .value_kind:     hidden_group_size_x
      - .offset:         214
        .size:           2
        .value_kind:     hidden_group_size_y
      - .offset:         216
        .size:           2
        .value_kind:     hidden_group_size_z
      - .offset:         218
        .size:           2
        .value_kind:     hidden_remainder_x
      - .offset:         220
        .size:           2
        .value_kind:     hidden_remainder_y
      - .offset:         222
        .size:           2
        .value_kind:     hidden_remainder_z
      - .offset:         240
        .size:           8
        .value_kind:     hidden_global_offset_x
      - .offset:         248
        .size:           8
        .value_kind:     hidden_global_offset_y
      - .offset:         256
        .size:           8
        .value_kind:     hidden_global_offset_z
      - .offset:         264
        .size:           2
        .value_kind:     hidden_grid_dims
      - .offset:         288
        .size:           8
        .value_kind:     hidden_multigrid_sync_arg
      - .offset:         320
        .size:           4
        .value_kind:     hidden_dynamic_lds_size
    .group_segment_fixed_size: 0
    .kernarg_segment_align: 8
    .kernarg_segment_size: 456
    .language:       OpenCL C
    .language_version:
      - 2
      - 0
    .max_flat_workgroup_size: 512
    .name:           _Z4mega6Params
    .private_segment_fixed_size: 0
    .sgpr_count:     108
    .sgpr_spill_count: 183
    .symbol:         _Z4mega6Params.kd
    .uniform_work_group_size: 1
    .uses_dynamic_stack: false
    .vgpr_count:     256
    .vgpr_spill_count: 0
    .wavefront_size: 64
